# seam prefetch extended: LN-epilogue residual tiles (x hi/lo planes) touched in the P6 and P10 seams
# baseline (speedup 1.0000x reference)
.Lseam_pf6:
	s_mov_b64 exec, s[10:11]
	v_readlane_b32 s78, v254, 20
	v_mov_b32_e32 v2, s78
	ds_read_b64 v[2:3], v2
	v_mbcnt_lo_u32_b32 v4, -1, 0
	v_mbcnt_hi_u32_b32 v4, -1, v4
	v_readlane_b32 s79, v252, 2
	v_readlane_b32 s82, v252, 8
	v_readlane_b32 s83, v254, 36
	s_waitcnt lgkmcnt(0)
	v_readfirstlane_b32 s80, v2
	v_readfirstlane_b32 s81, v3
	s_and_b32 s84, s79, 1
	s_lshl_b32 s84, s84, 2
	s_lshr_b32 s85, s79, 6
	s_add_i32 s84, s84, s85
	s_lshr_b32 s82, s82, 6
	s_add_i32 s82, s82, -1
	s_lshl_b32 s85, s82, 8
	s_add_i32 s85, s85, 0x21000
	s_mov_b32 m0, s85
	s_mul_i32 s86, s83, 0x800000
	s_mul_i32 s87, s84, 0x100000
	s_add_u32 s86, s86, s87
	s_add_u32 s86, s86, 0x16500000
	s_add_u32 s86, s80, s86
	s_addc_u32 s87, s81, 0
	v_lshrrev_b32_e32 v5, 1, v4
	v_lshl_add_u32 v5, s82, 5, v5
	v_mul_u32_u24_e32 v5, 0x1000, v5
	v_and_b32_e32 v6, 1, v4
	v_lshl_add_u32 v5, v6, 7, v5
	global_load_lds_dword v5, s[86:87]
	s_and_b32 s86, s79, 7
	s_lshr_b32 s86, s86, 1
	s_lshl_b32 s86, s86, 3
	s_bfe_u32 s87, s79, 0x30003
	s_add_i32 s79, s86, s87
	s_lshl_b32 s86, s79, 20
	s_lshl_b32 s87, s84, 9
	s_add_u32 s86, s86, s87
	s_add_u32 s86, s86, 0x28d00000
	s_lshl_b32 s87, s82, 16
	s_add_u32 s86, s86, s87
	s_add_u32 s86, s80, s86
	s_addc_u32 s87, s81, 0
	v_lshrrev_b32_e32 v5, 2, v4
	v_lshlrev_b32_e32 v5, 12, v5
	v_and_b32_e32 v6, 3, v4
	v_lshl_add_u32 v5, v6, 7, v5
	global_load_lds_dword v5, s[86:87]
	s_add_u32 s86, s86, 0x70000
	s_addc_u32 s87, s87, 0
	global_load_lds_dword v5, s[86:87]
	s_cmp_gt_u32 s82, 1
	s_cbranch_scc1 .Lseam_x6_a
	s_add_u32 s86, s86, 0x70000
	s_addc_u32 s87, s87, 0
	global_load_lds_dword v5, s[86:87]
.Lseam_x6_a:
	s_lshl_b32 s86, s79, 3
	s_add_i32 s86, s86, s84
	s_lshl_b32 s86, s86, 16
	s_add_u32 s86, s86, 0x79e00000
	s_lshl_b32 s87, s82, 13
	s_add_u32 s86, s86, s87
	s_add_u32 s86, s80, s86
	s_addc_u32 s87, s81, 0
	v_lshlrev_b32_e32 v5, 7, v4
	global_load_lds_dword v5, s[86:87]
	s_cmp_lg_u32 s82, 0
	s_cbranch_scc1 .Lseam_x6_b
	s_add_u32 s86, s86, 0xe000
	s_addc_u32 s87, s87, 0
	global_load_lds_dword v5, s[86:87]
.Lseam_x6_b:
	s_branch .LBB0_643
.Lseam_lead6:
	v_readlane_b32 s4, v252, 3
	s_waitcnt vmcnt(0) expcnt(0) lgkmcnt(0)
	s_nop 0
	v_mov_b32_e32 v0, s4
	ds_read_b32 v3, v0
	ds_read_b32 v2, v0 offset:4
	s_waitcnt lgkmcnt(1)
	v_cmp_ne_u32_e32 vcc, 0, v3
	s_cbranch_vccnz .LBB0_611
	v_readlane_b32 s6, v252, 0
	v_readlane_b32 s7, v252, 1
	s_load_dwordx2 s[4:5], s[6:7], 0x4
	s_waitcnt lgkmcnt(0)
	s_mul_i32 s4, s4, s56
	s_mul_i32 s4, s4, s5
	s_mov_b32 s5, 1
	s_branch .LBB0_599

.LBB0_877:
	v_readlane_b32 s2, v254, 38
	v_readlane_b32 s4, v252, 6
	s_add_i32 s2, s2, 8
	v_readlane_b32 s5, v252, 7
	s_cmp_lt_i32 s2, s5
	s_cselect_b64 s[12:13], -1, 0
	s_and_b64 s[4:5], s[10:11], s[12:13]
	s_andn2_b64 vcc, exec, s[4:5]
	s_cbranch_vccnz .LBB0_927
	s_waitcnt vmcnt(0)
	s_barrier
	s_mov_b64 s[10:11], exec
	v_readlane_b32 s4, v252, 4
	v_readlane_b32 s5, v252, 5
	s_and_b64 s[4:5], s[10:11], s[4:5]
	s_mov_b64 exec, s[4:5]
	s_cbranch_execz .Lseam_pf10
	s_branch .Lseam_lead10
.Lseam_pf10:
	s_mov_b64 exec, s[10:11]
	v_readlane_b32 s78, v254, 20
	v_mov_b32_e32 v2, s78
	ds_read_b64 v[2:3], v2
	v_mbcnt_lo_u32_b32 v4, -1, 0
	v_mbcnt_hi_u32_b32 v4, -1, v4
	v_readlane_b32 s79, v252, 2
	v_readlane_b32 s82, v252, 8
	v_readlane_b32 s83, v254, 36
	s_waitcnt lgkmcnt(0)
	v_readfirstlane_b32 s80, v2
	v_readfirstlane_b32 s81, v3
	s_and_b32 s84, s79, 1
	s_lshl_b32 s84, s84, 2
	s_lshr_b32 s85, s79, 6
	s_add_i32 s84, s84, s85
	s_lshr_b32 s82, s82, 6
	s_add_i32 s82, s82, -1
	s_lshl_b32 s85, s82, 8
	s_add_i32 s85, s85, 0x21000
	s_mov_b32 m0, s85
	s_and_b32 s86, s79, 7
	s_lshr_b32 s86, s86, 1
	s_lshl_b32 s86, s86, 3
	s_bfe_u32 s87, s79, 0x30003
	s_add_i32 s79, s86, s87
	s_lshl_b32 s86, s79, 20
	s_lshl_b32 s87, s84, 9
	s_add_u32 s86, s86, s87
	s_add_u32 s86, s86, 0x28d00000
	s_lshl_b32 s87, s82, 16
	s_add_u32 s86, s86, s87
	s_add_u32 s86, s80, s86
	s_addc_u32 s87, s81, 0
	v_lshrrev_b32_e32 v5, 2, v4
	v_lshlrev_b32_e32 v5, 12, v5
	v_and_b32_e32 v6, 3, v4
	v_lshl_add_u32 v5, v6, 7, v5
	global_load_lds_dword v5, s[86:87]
	s_add_u32 s86, s86, 0x70000
	s_addc_u32 s87, s87, 0
	global_load_lds_dword v5, s[86:87]
	s_cmp_gt_u32 s82, 1
	s_cbranch_scc1 .Lseam_x10_a
	s_add_u32 s86, s86, 0x70000
	s_addc_u32 s87, s87, 0
	global_load_lds_dword v5, s[86:87]
.Lseam_x10_a:
	s_branch .LBB0_926
.Lseam_lead10:
	v_readlane_b32 s4, v252, 3
	s_waitcnt vmcnt(0) expcnt(0) lgkmcnt(0)
	s_nop 0
	v_mov_b32_e32 v0, s4
	ds_read_b32 v3, v0
	ds_read_b32 v2, v0 offset:4
	s_waitcnt lgkmcnt(1)
	v_cmp_ne_u32_e32 vcc, 0, v3
	s_cbranch_vccnz .LBB0_894
	v_readlane_b32 s6, v252, 0
	v_readlane_b32 s7, v252, 1
	s_load_dwordx2 s[4:5], s[6:7], 0x4
	s_waitcnt lgkmcnt(0)
	s_mul_i32 s4, s4, s56
	s_mul_i32 s4, s4, s5
	s_mov_b32 s5, 1
	s_branch .LBB0_882
.LBB0_881:
	s_and_b64 vcc, exec, s[16:17]
	s_cbranch_vccnz .LBB0_889
